# dil_merge loop rewritten with next-token prefetch; top-k radix select ballot/popcount/compare on the scalar unit
# speedup vs baseline: 1.0127x; 1.0020x over previous
; DI void slc_block(const Params& p, int it, int tid, int wid, int lane) {
;     ...
;       const int j = lane;
;       const float4 pq = *reinterpret_cast<const float4*>(psrow + 4 * j);
;       const float sm = (j > 0 ? psrow[4 * j - 1] : 0.f) + pq.x + pq.y + pq.z + pq.w;
;       const bool forced = (j == 0) || (j == blk_t) || (j == blk_t - 1);
;       key = valid ? __float_as_uint(sm + (forced ? 1e4f : 0.f)) : 0u;
;     }
;     unsigned thr = 0u;
;     ...
;       const unsigned cand = thr | (1u << bit);
;       if (__popcll(__ballot(valid && key >= cand)) >= 16) thr = cand;
;     }
;     const unsigned long long gt = __ballot(valid && key > thr), eq = __ballot(valid && key == thr);
;     const int need = 16 - __popcll(gt);
;     const int idx_eq = (int)__builtin_amdgcn_mbcnt_hi((unsigned)(eq >> 32), __builtin_amdgcn_mbcnt_lo((unsigned)eq, 0u));
;     msel[k] = __ballot(valid && (key > thr || (key == thr && idx_eq < need)));
.LBB0_173:
	s_or_b64 exec, exec, s[16:17]
	s_waitcnt vmcnt(0)
	v_add_f32_e32 v2, v2, v8
	v_add_f32_e32 v2, v3, v2
	v_add_f32_e32 v2, v4, v2
	v_add_f32_e32 v2, v5, v2
	v_add_f32_e32 v2, v0, v2
	v_cndmask_b32_e64 v2, 0, v2, s[14:15]
	s_brev_b32 s10, -4
	v_cmp_lt_u32_e32 vcc, s10, v2
	s_and_b64 s[10:11], s[14:15], vcc
	s_and_b64 s[10:11], s[10:11], exec
	s_bcnt1_i32_b64 s10, s[10:11]
	s_cmp_gt_u32 s10, 15
	s_cselect_b32 s16, 2.0, 0
	s_or_b32 s17, s16, 0x20000000
	v_cmp_le_u32_e32 vcc, s17, v2
	s_and_b64 s[10:11], s[14:15], vcc
	s_and_b64 s[10:11], s[10:11], exec
	s_bcnt1_i32_b64 s10, s[10:11]
	s_cmp_gt_u32 s10, 15
	s_cselect_b32 s16, s17, s16
	s_or_b32 s17, s16, 0x10000000
	v_cmp_le_u32_e32 vcc, s17, v2
	s_and_b64 s[10:11], s[14:15], vcc
	s_and_b64 s[10:11], s[10:11], exec
	s_bcnt1_i32_b64 s10, s[10:11]
	s_cmp_gt_u32 s10, 15
	s_cselect_b32 s16, s17, s16
	s_or_b32 s17, s16, 0x8000000
	v_cmp_le_u32_e32 vcc, s17, v2
	s_and_b64 s[10:11], s[14:15], vcc
	s_and_b64 s[10:11], s[10:11], exec
	s_bcnt1_i32_b64 s10, s[10:11]
	s_cmp_gt_u32 s10, 15
	s_cselect_b32 s16, s17, s16
	s_or_b32 s17, s16, 0x4000000
	v_cmp_le_u32_e32 vcc, s17, v2
	s_and_b64 s[10:11], s[14:15], vcc
	s_and_b64 s[10:11], s[10:11], exec
	s_bcnt1_i32_b64 s10, s[10:11]
	s_cmp_gt_u32 s10, 15
	s_cselect_b32 s16, s17, s16
	s_or_b32 s17, s16, 0x2000000
	v_cmp_le_u32_e32 vcc, s17, v2
	s_and_b64 s[10:11], s[14:15], vcc
	s_and_b64 s[10:11], s[10:11], exec
	s_bcnt1_i32_b64 s10, s[10:11]
	s_cmp_gt_u32 s10, 15
	s_cselect_b32 s16, s17, s16
	s_or_b32 s17, s16, 0x1000000
	v_cmp_le_u32_e32 vcc, s17, v2
	s_and_b64 s[10:11], s[14:15], vcc
	s_and_b64 s[10:11], s[10:11], exec
	s_bcnt1_i32_b64 s10, s[10:11]
	s_cmp_gt_u32 s10, 15
	s_cselect_b32 s16, s17, s16
	s_or_b32 s17, s16, 0x800000
	v_cmp_le_u32_e32 vcc, s17, v2
	s_and_b64 s[10:11], s[14:15], vcc
	s_and_b64 s[10:11], s[10:11], exec
	s_bcnt1_i32_b64 s10, s[10:11]
	s_cmp_gt_u32 s10, 15
	s_cselect_b32 s16, s17, s16
	s_or_b32 s17, s16, 0x400000
	v_cmp_le_u32_e32 vcc, s17, v2
	s_and_b64 s[10:11], s[14:15], vcc
	s_and_b64 s[10:11], s[10:11], exec
	s_bcnt1_i32_b64 s10, s[10:11]
	s_cmp_gt_u32 s10, 15
	s_cselect_b32 s16, s17, s16
	s_or_b32 s17, s16, 0x200000
	v_cmp_le_u32_e32 vcc, s17, v2
	s_and_b64 s[10:11], s[14:15], vcc
	s_and_b64 s[10:11], s[10:11], exec
	s_bcnt1_i32_b64 s10, s[10:11]
	s_cmp_gt_u32 s10, 15
	s_cselect_b32 s16, s17, s16
	s_or_b32 s17, s16, 0x100000
	v_cmp_le_u32_e32 vcc, s17, v2
	s_and_b64 s[10:11], s[14:15], vcc
	s_and_b64 s[10:11], s[10:11], exec
	s_bcnt1_i32_b64 s10, s[10:11]
	s_cmp_gt_u32 s10, 15
	s_cselect_b32 s16, s17, s16
	s_or_b32 s17, s16, 0x80000
	v_cmp_le_u32_e32 vcc, s17, v2
	s_and_b64 s[10:11], s[14:15], vcc
	s_and_b64 s[10:11], s[10:11], exec
	s_bcnt1_i32_b64 s10, s[10:11]
	s_cmp_gt_u32 s10, 15
	s_cselect_b32 s16, s17, s16
	s_or_b32 s17, s16, 0x40000
	v_cmp_le_u32_e32 vcc, s17, v2
	s_and_b64 s[10:11], s[14:15], vcc
	s_and_b64 s[10:11], s[10:11], exec
	s_bcnt1_i32_b64 s10, s[10:11]
	s_cmp_gt_u32 s10, 15
	s_cselect_b32 s16, s17, s16
	s_or_b32 s17, s16, 0x20000
	v_cmp_le_u32_e32 vcc, s17, v2
	s_and_b64 s[10:11], s[14:15], vcc
	s_and_b64 s[10:11], s[10:11], exec
	s_bcnt1_i32_b64 s10, s[10:11]
	s_cmp_gt_u32 s10, 15
	s_cselect_b32 s16, s17, s16
	s_or_b32 s17, s16, 0x10000
	v_cmp_le_u32_e32 vcc, s17, v2
	s_and_b64 s[10:11], s[14:15], vcc
	s_and_b64 s[10:11], s[10:11], exec
	s_bcnt1_i32_b64 s10, s[10:11]
	s_cmp_gt_u32 s10, 15
	s_cselect_b32 s16, s17, s16
	s_or_b32 s17, s16, 0x8000
	v_cmp_le_u32_e32 vcc, s17, v2
	s_and_b64 s[10:11], s[14:15], vcc
	s_and_b64 s[10:11], s[10:11], exec
	s_bcnt1_i32_b64 s10, s[10:11]
	s_cmp_gt_u32 s10, 15
	s_cselect_b32 s16, s17, s16
	s_or_b32 s17, s16, 0x4000
	v_cmp_le_u32_e32 vcc, s17, v2
	s_and_b64 s[10:11], s[14:15], vcc
; DI void slc_block(const Params& p, int it, int tid, int wid, int lane) {
;     ...
;     unsigned thr = 0u;
;     ...
;       const unsigned cand = thr | (1u << bit);
;       if (__popcll(__ballot(valid && key >= cand)) >= 16) thr = cand;
;     }
;     const unsigned long long gt = __ballot(valid && key > thr), eq = __ballot(valid && key == thr);
;     const int need = 16 - __popcll(gt);
;     const int idx_eq = (int)__builtin_amdgcn_mbcnt_hi((unsigned)(eq >> 32), __builtin_amdgcn_mbcnt_lo((unsigned)eq, 0u));
;     msel[k] = __ballot(valid && (key > thr || (key == thr && idx_eq < need)));
;   }
	s_and_b64 s[10:11], s[10:11], exec
	s_bcnt1_i32_b64 s10, s[10:11]
	s_cmp_gt_u32 s10, 15
	s_cselect_b32 s16, s17, s16
	s_or_b32 s17, s16, 0x2000
	v_cmp_le_u32_e32 vcc, s17, v2
	s_and_b64 s[10:11], s[14:15], vcc
	s_and_b64 s[10:11], s[10:11], exec
	s_bcnt1_i32_b64 s10, s[10:11]
	s_cmp_gt_u32 s10, 15
	s_cselect_b32 s16, s17, s16
	s_or_b32 s17, s16, 0x1000
	v_cmp_le_u32_e32 vcc, s17, v2
	s_and_b64 s[10:11], s[14:15], vcc
	s_and_b64 s[10:11], s[10:11], exec
	s_bcnt1_i32_b64 s10, s[10:11]
	s_cmp_gt_u32 s10, 15
	s_cselect_b32 s16, s17, s16
	s_or_b32 s17, s16, 0x800
	v_cmp_le_u32_e32 vcc, s17, v2
	s_and_b64 s[10:11], s[14:15], vcc
	s_and_b64 s[10:11], s[10:11], exec
	s_bcnt1_i32_b64 s10, s[10:11]
	s_cmp_gt_u32 s10, 15
	s_cselect_b32 s16, s17, s16
	s_or_b32 s17, s16, 0x400
	v_cmp_le_u32_e32 vcc, s17, v2
	s_and_b64 s[10:11], s[14:15], vcc
	s_and_b64 s[10:11], s[10:11], exec
	s_bcnt1_i32_b64 s10, s[10:11]
	s_cmp_gt_u32 s10, 15
	s_cselect_b32 s16, s17, s16
	s_or_b32 s17, s16, 0x200
	v_cmp_le_u32_e32 vcc, s17, v2
	s_and_b64 s[10:11], s[14:15], vcc
	s_and_b64 s[10:11], s[10:11], exec
	s_bcnt1_i32_b64 s10, s[10:11]
	s_cmp_gt_u32 s10, 15
	s_cselect_b32 s16, s17, s16
	s_or_b32 s17, s16, 0x100
	v_cmp_le_u32_e32 vcc, s17, v2
	s_and_b64 s[10:11], s[14:15], vcc
	s_and_b64 s[10:11], s[10:11], exec
	s_bcnt1_i32_b64 s10, s[10:11]
	s_cmp_gt_u32 s10, 15
	s_cselect_b32 s16, s17, s16
	s_or_b32 s17, s16, 0x80
	v_cmp_le_u32_e32 vcc, s17, v2
	s_and_b64 s[10:11], s[14:15], vcc
	s_and_b64 s[10:11], s[10:11], exec
	s_bcnt1_i32_b64 s10, s[10:11]
	s_cmp_gt_u32 s10, 15
	s_cselect_b32 s16, s17, s16
	s_or_b32 s17, s16, 64
	v_cmp_le_u32_e32 vcc, s17, v2
	s_and_b64 s[10:11], s[14:15], vcc
	s_and_b64 s[10:11], s[10:11], exec
	s_bcnt1_i32_b64 s10, s[10:11]
	s_cmp_gt_u32 s10, 15
	s_cselect_b32 s16, s17, s16
	s_or_b32 s17, s16, 32
	v_cmp_le_u32_e32 vcc, s17, v2
	s_and_b64 s[10:11], s[14:15], vcc
	s_and_b64 s[10:11], s[10:11], exec
	s_bcnt1_i32_b64 s10, s[10:11]
	s_cmp_gt_u32 s10, 15
	s_cselect_b32 s16, s17, s16
	s_or_b32 s17, s16, 16
	v_cmp_le_u32_e32 vcc, s17, v2
	s_and_b64 s[10:11], s[14:15], vcc
	s_and_b64 s[10:11], s[10:11], exec
	s_bcnt1_i32_b64 s10, s[10:11]
	s_cmp_gt_u32 s10, 15
	s_cselect_b32 s16, s17, s16
	s_or_b32 s17, s16, 8
	v_cmp_le_u32_e32 vcc, s17, v2
	s_and_b64 s[10:11], s[14:15], vcc
	s_and_b64 s[10:11], s[10:11], exec
	s_bcnt1_i32_b64 s10, s[10:11]
	s_cmp_gt_u32 s10, 15
	s_cselect_b32 s16, s17, s16
	s_or_b32 s17, s16, 4
	v_cmp_le_u32_e32 vcc, s17, v2
	s_and_b64 s[10:11], s[14:15], vcc
	s_and_b64 s[10:11], s[10:11], exec
	s_bcnt1_i32_b64 s10, s[10:11]
	s_cmp_gt_u32 s10, 15
	s_cselect_b32 s16, s17, s16
	s_or_b32 s17, s16, 2
	v_cmp_le_u32_e32 vcc, s17, v2
	s_and_b64 s[10:11], s[14:15], vcc
	s_and_b64 s[10:11], s[10:11], exec
	s_bcnt1_i32_b64 s10, s[10:11]
	s_cmp_gt_u32 s10, 15
	s_cselect_b32 s16, s17, s16
	s_or_b32 s17, s16, 1
	v_cmp_le_u32_e32 vcc, s17, v2
	s_and_b64 s[10:11], s[14:15], vcc
	s_and_b64 s[10:11], s[10:11], exec
	s_bcnt1_i32_b64 s10, s[10:11]
	s_cmp_gt_u32 s10, 15
	s_cselect_b32 s20, s17, s16
	v_cmp_lt_u32_e32 vcc, s20, v2
	s_and_b64 s[10:11], s[14:15], vcc
	v_cmp_eq_u32_e64 s[20:21], s20, v2
	v_cndmask_b32_e64 v3, 0, 1, s[10:11]
	s_and_b64 s[10:11], s[14:15], s[20:21]
	v_cndmask_b32_e64 v2, 0, 1, s[10:11]
	v_cmp_ne_u32_e64 s[16:17], 0, v3
	v_cmp_ne_u32_e64 s[22:23], 0, v2
	s_bcnt1_i32_b64 s10, s[16:17]
	s_sub_i32 s10, 16, s10
	v_mbcnt_lo_u32_b32 v2, s22, 0
	v_mbcnt_hi_u32_b32 v2, s23, v2
	v_cmp_gt_i32_e64 s[16:17], s10, v2
	s_and_b64 s[10:11], s[20:21], s[16:17]
	v_cndmask_b32_e64 v2, 0, 1, s[10:11]
	v_cndmask_b32_e64 v3, 0, 1, s[14:15]
	s_or_b64 vcc, s[12:13], vcc
	v_cndmask_b32_e32 v2, v2, v3, vcc
	v_and_b32_e32 v2, 1, v2
	v_cmp_ne_u32_e64 s[30:31], 0, v2
	s_mov_b64 s[16:17], 0

; DI void slc_block(const Params& p, int it, int tid, int wid, int lane) {
;     ...
;     {
;       const int j = lane;
;       const float4 pq = *reinterpret_cast<const float4*>(psrow + 4 * j);
;       const float sm = (j > 0 ? psrow[4 * j - 1] : 0.f) + pq.x + pq.y + pq.z + pq.w;
.LBB0_179:
	s_or_b64 exec, exec, s[2:3]
	s_waitcnt vmcnt(0)
; DI void slc_block(const Params& p, int it, int tid, int wid, int lane) {
;     ...
;       const int j = lane;
;       const float4 pq = *reinterpret_cast<const float4*>(psrow + 4 * j);
;       const float sm = (j > 0 ? psrow[4 * j - 1] : 0.f) + pq.x + pq.y + pq.z + pq.w;
;       const bool forced = (j == 0) || (j == blk_t) || (j == blk_t - 1);
;       key = valid ? __float_as_uint(sm + (forced ? 1e4f : 0.f)) : 0u;
;     }
;     unsigned thr = 0u;
;     ...
;       const unsigned cand = thr | (1u << bit);
;       if (__popcll(__ballot(valid && key >= cand)) >= 16) thr = cand;
;     }
;     const unsigned long long gt = __ballot(valid && key > thr), eq = __ballot(valid && key == thr);
;     const int need = 16 - __popcll(gt);
;     const int idx_eq = (int)__builtin_amdgcn_mbcnt_hi((unsigned)(eq >> 32), __builtin_amdgcn_mbcnt_lo((unsigned)eq, 0u));
;     msel[k] = __ballot(valid && (key > thr || (key == thr && idx_eq < need)));
;   }
	v_add_f32_e32 v2, v2, v9
	v_add_f32_e32 v2, v3, v2
	v_add_f32_e32 v2, v4, v2
	v_add_f32_e32 v2, v5, v2
	v_add_f32_e32 v2, v0, v2
	v_cndmask_b32_e64 v2, 0, v2, s[14:15]
	s_brev_b32 s2, -4
	v_cmp_lt_u32_e32 vcc, s2, v2
	s_and_b64 s[2:3], s[14:15], vcc
	s_and_b64 s[2:3], s[2:3], exec
	s_bcnt1_i32_b64 s2, s[2:3]
	s_cmp_gt_u32 s2, 15
	s_cselect_b32 s10, 2.0, 0
	s_or_b32 s11, s10, 0x20000000
	v_cmp_le_u32_e32 vcc, s11, v2
	s_and_b64 s[2:3], s[14:15], vcc
	s_and_b64 s[2:3], s[2:3], exec
	s_bcnt1_i32_b64 s2, s[2:3]
	s_cmp_gt_u32 s2, 15
	s_cselect_b32 s10, s11, s10
	s_or_b32 s11, s10, 0x10000000
	v_cmp_le_u32_e32 vcc, s11, v2
	s_and_b64 s[2:3], s[14:15], vcc
	s_and_b64 s[2:3], s[2:3], exec
	s_bcnt1_i32_b64 s2, s[2:3]
	s_cmp_gt_u32 s2, 15
	s_cselect_b32 s10, s11, s10
	s_or_b32 s11, s10, 0x8000000
	v_cmp_le_u32_e32 vcc, s11, v2
	s_and_b64 s[2:3], s[14:15], vcc
	s_and_b64 s[2:3], s[2:3], exec
	s_bcnt1_i32_b64 s2, s[2:3]
	s_cmp_gt_u32 s2, 15
	s_cselect_b32 s10, s11, s10
	s_or_b32 s11, s10, 0x4000000
	v_cmp_le_u32_e32 vcc, s11, v2
	s_and_b64 s[2:3], s[14:15], vcc
	s_and_b64 s[2:3], s[2:3], exec
	s_bcnt1_i32_b64 s2, s[2:3]
	s_cmp_gt_u32 s2, 15
	s_cselect_b32 s10, s11, s10
	s_or_b32 s11, s10, 0x2000000
	v_cmp_le_u32_e32 vcc, s11, v2
	s_and_b64 s[2:3], s[14:15], vcc
	s_and_b64 s[2:3], s[2:3], exec
	s_bcnt1_i32_b64 s2, s[2:3]
	s_cmp_gt_u32 s2, 15
	s_cselect_b32 s10, s11, s10
	s_or_b32 s11, s10, 0x1000000
	v_cmp_le_u32_e32 vcc, s11, v2
	s_and_b64 s[2:3], s[14:15], vcc
	s_and_b64 s[2:3], s[2:3], exec
	s_bcnt1_i32_b64 s2, s[2:3]
	s_cmp_gt_u32 s2, 15
	s_cselect_b32 s10, s11, s10
	s_or_b32 s11, s10, 0x800000
	v_cmp_le_u32_e32 vcc, s11, v2
	s_and_b64 s[2:3], s[14:15], vcc
	s_and_b64 s[2:3], s[2:3], exec
	s_bcnt1_i32_b64 s2, s[2:3]
	s_cmp_gt_u32 s2, 15
	s_cselect_b32 s10, s11, s10
	s_or_b32 s11, s10, 0x400000
	v_cmp_le_u32_e32 vcc, s11, v2
	s_and_b64 s[2:3], s[14:15], vcc
	s_and_b64 s[2:3], s[2:3], exec
	s_bcnt1_i32_b64 s2, s[2:3]
	s_cmp_gt_u32 s2, 15
	s_cselect_b32 s10, s11, s10
	s_or_b32 s11, s10, 0x200000
	v_cmp_le_u32_e32 vcc, s11, v2
	s_and_b64 s[2:3], s[14:15], vcc
	s_and_b64 s[2:3], s[2:3], exec
	s_bcnt1_i32_b64 s2, s[2:3]
	s_cmp_gt_u32 s2, 15
	s_cselect_b32 s10, s11, s10
	s_or_b32 s11, s10, 0x100000
	v_cmp_le_u32_e32 vcc, s11, v2
	s_and_b64 s[2:3], s[14:15], vcc
	s_and_b64 s[2:3], s[2:3], exec
	s_bcnt1_i32_b64 s2, s[2:3]
	s_cmp_gt_u32 s2, 15
	s_cselect_b32 s10, s11, s10
	s_or_b32 s11, s10, 0x80000
	v_cmp_le_u32_e32 vcc, s11, v2
	s_and_b64 s[2:3], s[14:15], vcc
	s_and_b64 s[2:3], s[2:3], exec
	s_bcnt1_i32_b64 s2, s[2:3]
	s_cmp_gt_u32 s2, 15
	s_cselect_b32 s10, s11, s10
	s_or_b32 s11, s10, 0x40000
	v_cmp_le_u32_e32 vcc, s11, v2
	s_and_b64 s[2:3], s[14:15], vcc
	s_and_b64 s[2:3], s[2:3], exec
	s_bcnt1_i32_b64 s2, s[2:3]
	s_cmp_gt_u32 s2, 15
	s_cselect_b32 s10, s11, s10
	s_or_b32 s11, s10, 0x20000
	v_cmp_le_u32_e32 vcc, s11, v2
	s_and_b64 s[2:3], s[14:15], vcc
	s_and_b64 s[2:3], s[2:3], exec
	s_bcnt1_i32_b64 s2, s[2:3]
	s_cmp_gt_u32 s2, 15
	s_cselect_b32 s10, s11, s10
	s_or_b32 s11, s10, 0x10000
	v_cmp_le_u32_e32 vcc, s11, v2
	s_and_b64 s[2:3], s[14:15], vcc
	s_and_b64 s[2:3], s[2:3], exec
	s_bcnt1_i32_b64 s2, s[2:3]
	s_cmp_gt_u32 s2, 15
	s_cselect_b32 s10, s11, s10
	s_or_b32 s11, s10, 0x8000
	v_cmp_le_u32_e32 vcc, s11, v2
	s_and_b64 s[2:3], s[14:15], vcc
	s_and_b64 s[2:3], s[2:3], exec
	s_bcnt1_i32_b64 s2, s[2:3]
	s_cmp_gt_u32 s2, 15
	s_cselect_b32 s10, s11, s10
	s_or_b32 s11, s10, 0x4000
	v_cmp_le_u32_e32 vcc, s11, v2
	s_and_b64 s[2:3], s[14:15], vcc
	s_and_b64 s[2:3], s[2:3], exec
	s_bcnt1_i32_b64 s2, s[2:3]
	s_cmp_gt_u32 s2, 15
	s_cselect_b32 s10, s11, s10
	s_or_b32 s11, s10, 0x2000
	v_cmp_le_u32_e32 vcc, s11, v2
	s_and_b64 s[2:3], s[14:15], vcc
	s_and_b64 s[2:3], s[2:3], exec
	s_bcnt1_i32_b64 s2, s[2:3]
	s_cmp_gt_u32 s2, 15
	s_cselect_b32 s10, s11, s10
	s_or_b32 s11, s10, 0x1000
	v_cmp_le_u32_e32 vcc, s11, v2
	s_and_b64 s[2:3], s[14:15], vcc
	s_and_b64 s[2:3], s[2:3], exec
	s_bcnt1_i32_b64 s2, s[2:3]
	s_cmp_gt_u32 s2, 15
	s_cselect_b32 s10, s11, s10
	s_or_b32 s11, s10, 0x800
	v_cmp_le_u32_e32 vcc, s11, v2
	s_and_b64 s[2:3], s[14:15], vcc
	s_and_b64 s[2:3], s[2:3], exec
	s_bcnt1_i32_b64 s2, s[2:3]
	s_cmp_gt_u32 s2, 15
	s_cselect_b32 s10, s11, s10
	s_or_b32 s11, s10, 0x400
	v_cmp_le_u32_e32 vcc, s11, v2
	s_and_b64 s[2:3], s[14:15], vcc
	s_and_b64 s[2:3], s[2:3], exec
	s_bcnt1_i32_b64 s2, s[2:3]
	s_cmp_gt_u32 s2, 15
	s_cselect_b32 s10, s11, s10
	s_or_b32 s11, s10, 0x200
	v_cmp_le_u32_e32 vcc, s11, v2
	s_and_b64 s[2:3], s[14:15], vcc
	s_and_b64 s[2:3], s[2:3], exec
	s_bcnt1_i32_b64 s2, s[2:3]
	s_cmp_gt_u32 s2, 15
	s_cselect_b32 s10, s11, s10
	s_or_b32 s11, s10, 0x100
	v_cmp_le_u32_e32 vcc, s11, v2
	s_and_b64 s[2:3], s[14:15], vcc
	s_and_b64 s[2:3], s[2:3], exec
	s_bcnt1_i32_b64 s2, s[2:3]
	s_cmp_gt_u32 s2, 15
	s_cselect_b32 s10, s11, s10
	s_or_b32 s11, s10, 0x80
	v_cmp_le_u32_e32 vcc, s11, v2
	s_and_b64 s[2:3], s[14:15], vcc
	s_and_b64 s[2:3], s[2:3], exec
	s_bcnt1_i32_b64 s2, s[2:3]
	s_cmp_gt_u32 s2, 15
	s_cselect_b32 s10, s11, s10
	s_or_b32 s11, s10, 64
	v_cmp_le_u32_e32 vcc, s11, v2
	s_and_b64 s[2:3], s[14:15], vcc
	s_and_b64 s[2:3], s[2:3], exec
	s_bcnt1_i32_b64 s2, s[2:3]
	s_cmp_gt_u32 s2, 15
	s_cselect_b32 s10, s11, s10
	s_or_b32 s11, s10, 32
	v_cmp_le_u32_e32 vcc, s11, v2
	s_and_b64 s[2:3], s[14:15], vcc
	s_and_b64 s[2:3], s[2:3], exec
	s_bcnt1_i32_b64 s2, s[2:3]
	s_cmp_gt_u32 s2, 15
	s_cselect_b32 s10, s11, s10
	s_or_b32 s11, s10, 16
	v_cmp_le_u32_e32 vcc, s11, v2
	s_and_b64 s[2:3], s[14:15], vcc
	s_and_b64 s[2:3], s[2:3], exec
	s_bcnt1_i32_b64 s2, s[2:3]
	s_cmp_gt_u32 s2, 15
	s_cselect_b32 s10, s11, s10
	s_or_b32 s11, s10, 8
	v_cmp_le_u32_e32 vcc, s11, v2
	s_and_b64 s[2:3], s[14:15], vcc
	s_and_b64 s[2:3], s[2:3], exec
	s_bcnt1_i32_b64 s2, s[2:3]
	s_cmp_gt_u32 s2, 15
	s_cselect_b32 s10, s11, s10
	s_or_b32 s11, s10, 4
	v_cmp_le_u32_e32 vcc, s11, v2
	s_and_b64 s[2:3], s[14:15], vcc
	s_and_b64 s[2:3], s[2:3], exec
	s_bcnt1_i32_b64 s2, s[2:3]
	s_cmp_gt_u32 s2, 15
	s_cselect_b32 s10, s11, s10
	s_or_b32 s11, s10, 2
	v_cmp_le_u32_e32 vcc, s11, v2
	s_and_b64 s[2:3], s[14:15], vcc
	s_and_b64 s[2:3], s[2:3], exec
	s_bcnt1_i32_b64 s2, s[2:3]
	s_cmp_gt_u32 s2, 15
	s_cselect_b32 s10, s11, s10
	s_or_b32 s11, s10, 1
	v_cmp_le_u32_e32 vcc, s11, v2
	s_and_b64 s[2:3], s[14:15], vcc
	s_and_b64 s[2:3], s[2:3], exec
	s_bcnt1_i32_b64 s2, s[2:3]
	s_cmp_gt_u32 s2, 15
	s_cselect_b32 s10, s11, s10
	v_cmp_lt_u32_e32 vcc, s10, v2
	s_and_b64 s[2:3], s[14:15], vcc
	v_cmp_eq_u32_e64 s[22:23], s10, v2
	v_cndmask_b32_e64 v3, 0, 1, s[2:3]
	s_and_b64 s[2:3], s[14:15], s[22:23]
	v_cndmask_b32_e64 v2, 0, 1, s[2:3]
	v_cmp_ne_u32_e64 s[20:21], 0, v3
	v_cmp_ne_u32_e64 s[24:25], 0, v2
	s_bcnt1_i32_b64 s2, s[20:21]
	s_sub_i32 s2, 16, s2
	v_mbcnt_lo_u32_b32 v2, s24, 0
	v_mbcnt_hi_u32_b32 v2, s25, v2
	v_cmp_gt_i32_e64 s[20:21], s2, v2
	s_and_b64 s[2:3], s[22:23], s[20:21]
	v_cndmask_b32_e64 v2, 0, 1, s[2:3]
	s_or_b64 vcc, s[12:13], vcc
	v_cndmask_b32_e32 v2, v2, v8, vcc
	v_and_b32_e32 v2, 1, v2
	v_cmp_ne_u32_e64 s[58:59], 0, v2

; DI void slc_block(const Params& p, int it, int tid, int wid, int lane) {
;     ...
;     {
;       const int j = lane;
;       const float4 pq = *reinterpret_cast<const float4*>(psrow + 4 * j);
;       const float sm = (j > 0 ? psrow[4 * j - 1] : 0.f) + pq.x + pq.y + pq.z + pq.w;
.LBB0_183:
	s_or_b64 exec, exec, s[2:3]
	s_waitcnt vmcnt(0)
; DI void slc_block(const Params& p, int it, int tid, int wid, int lane) {
;     ...
;       const int j = lane;
;       const float4 pq = *reinterpret_cast<const float4*>(psrow + 4 * j);
;       const float sm = (j > 0 ? psrow[4 * j - 1] : 0.f) + pq.x + pq.y + pq.z + pq.w;
;       const bool forced = (j == 0) || (j == blk_t) || (j == blk_t - 1);
;       key = valid ? __float_as_uint(sm + (forced ? 1e4f : 0.f)) : 0u;
;     }
;     unsigned thr = 0u;
;     ...
;       const unsigned cand = thr | (1u << bit);
;       if (__popcll(__ballot(valid && key >= cand)) >= 16) thr = cand;
;     }
;     const unsigned long long gt = __ballot(valid && key > thr), eq = __ballot(valid && key == thr);
;     const int need = 16 - __popcll(gt);
;     const int idx_eq = (int)__builtin_amdgcn_mbcnt_hi((unsigned)(eq >> 32), __builtin_amdgcn_mbcnt_lo((unsigned)eq, 0u));
;     msel[k] = __ballot(valid && (key > thr || (key == thr && idx_eq < need)));
;   }
	v_add_f32_e32 v2, v2, v9
	v_add_f32_e32 v2, v3, v2
	v_add_f32_e32 v2, v4, v2
	v_add_f32_e32 v2, v5, v2
	v_add_f32_e32 v2, v0, v2
	v_cndmask_b32_e64 v2, 0, v2, s[14:15]
	s_brev_b32 s2, -4
	v_cmp_lt_u32_e32 vcc, s2, v2
	s_and_b64 s[2:3], s[14:15], vcc
	s_and_b64 s[2:3], s[2:3], exec
	s_bcnt1_i32_b64 s2, s[2:3]
	s_cmp_gt_u32 s2, 15
	s_cselect_b32 s10, 2.0, 0
	s_or_b32 s11, s10, 0x20000000
	v_cmp_le_u32_e32 vcc, s11, v2
	s_and_b64 s[2:3], s[14:15], vcc
	s_and_b64 s[2:3], s[2:3], exec
	s_bcnt1_i32_b64 s2, s[2:3]
	s_cmp_gt_u32 s2, 15
	s_cselect_b32 s10, s11, s10
	s_or_b32 s11, s10, 0x10000000
	v_cmp_le_u32_e32 vcc, s11, v2
	s_and_b64 s[2:3], s[14:15], vcc
	s_and_b64 s[2:3], s[2:3], exec
	s_bcnt1_i32_b64 s2, s[2:3]
	s_cmp_gt_u32 s2, 15
	s_cselect_b32 s10, s11, s10
	s_or_b32 s11, s10, 0x8000000
	v_cmp_le_u32_e32 vcc, s11, v2
	s_and_b64 s[2:3], s[14:15], vcc
	s_and_b64 s[2:3], s[2:3], exec
	s_bcnt1_i32_b64 s2, s[2:3]
	s_cmp_gt_u32 s2, 15
	s_cselect_b32 s10, s11, s10
	s_or_b32 s11, s10, 0x4000000
	v_cmp_le_u32_e32 vcc, s11, v2
	s_and_b64 s[2:3], s[14:15], vcc
	s_and_b64 s[2:3], s[2:3], exec
	s_bcnt1_i32_b64 s2, s[2:3]
	s_cmp_gt_u32 s2, 15
	s_cselect_b32 s10, s11, s10
	s_or_b32 s11, s10, 0x2000000
	v_cmp_le_u32_e32 vcc, s11, v2
	s_and_b64 s[2:3], s[14:15], vcc
	s_and_b64 s[2:3], s[2:3], exec
	s_bcnt1_i32_b64 s2, s[2:3]
	s_cmp_gt_u32 s2, 15
	s_cselect_b32 s10, s11, s10
	s_or_b32 s11, s10, 0x1000000
	v_cmp_le_u32_e32 vcc, s11, v2
	s_and_b64 s[2:3], s[14:15], vcc
	s_and_b64 s[2:3], s[2:3], exec
	s_bcnt1_i32_b64 s2, s[2:3]
	s_cmp_gt_u32 s2, 15
	s_cselect_b32 s10, s11, s10
	s_or_b32 s11, s10, 0x800000
	v_cmp_le_u32_e32 vcc, s11, v2
	s_and_b64 s[2:3], s[14:15], vcc
	s_and_b64 s[2:3], s[2:3], exec
	s_bcnt1_i32_b64 s2, s[2:3]
	s_cmp_gt_u32 s2, 15
	s_cselect_b32 s10, s11, s10
	s_or_b32 s11, s10, 0x400000
	v_cmp_le_u32_e32 vcc, s11, v2
	s_and_b64 s[2:3], s[14:15], vcc
	s_and_b64 s[2:3], s[2:3], exec
	s_bcnt1_i32_b64 s2, s[2:3]
	s_cmp_gt_u32 s2, 15
	s_cselect_b32 s10, s11, s10
	s_or_b32 s11, s10, 0x200000
	v_cmp_le_u32_e32 vcc, s11, v2
	s_and_b64 s[2:3], s[14:15], vcc
	s_and_b64 s[2:3], s[2:3], exec
	s_bcnt1_i32_b64 s2, s[2:3]
	s_cmp_gt_u32 s2, 15
	s_cselect_b32 s10, s11, s10
	s_or_b32 s11, s10, 0x100000
	v_cmp_le_u32_e32 vcc, s11, v2
	s_and_b64 s[2:3], s[14:15], vcc
	s_and_b64 s[2:3], s[2:3], exec
	s_bcnt1_i32_b64 s2, s[2:3]
	s_cmp_gt_u32 s2, 15
	s_cselect_b32 s10, s11, s10
	s_or_b32 s11, s10, 0x80000
	v_cmp_le_u32_e32 vcc, s11, v2
	s_and_b64 s[2:3], s[14:15], vcc
	s_and_b64 s[2:3], s[2:3], exec
	s_bcnt1_i32_b64 s2, s[2:3]
	s_cmp_gt_u32 s2, 15
	s_cselect_b32 s10, s11, s10
	s_or_b32 s11, s10, 0x40000
	v_cmp_le_u32_e32 vcc, s11, v2
	s_and_b64 s[2:3], s[14:15], vcc
	s_and_b64 s[2:3], s[2:3], exec
	s_bcnt1_i32_b64 s2, s[2:3]
	s_cmp_gt_u32 s2, 15
	s_cselect_b32 s10, s11, s10
	s_or_b32 s11, s10, 0x20000
	v_cmp_le_u32_e32 vcc, s11, v2
	s_and_b64 s[2:3], s[14:15], vcc
	s_and_b64 s[2:3], s[2:3], exec
	s_bcnt1_i32_b64 s2, s[2:3]
	s_cmp_gt_u32 s2, 15
	s_cselect_b32 s10, s11, s10
	s_or_b32 s11, s10, 0x10000
	v_cmp_le_u32_e32 vcc, s11, v2
	s_and_b64 s[2:3], s[14:15], vcc
	s_and_b64 s[2:3], s[2:3], exec
	s_bcnt1_i32_b64 s2, s[2:3]
	s_cmp_gt_u32 s2, 15
	s_cselect_b32 s10, s11, s10
	s_or_b32 s11, s10, 0x8000
	v_cmp_le_u32_e32 vcc, s11, v2
	s_and_b64 s[2:3], s[14:15], vcc
	s_and_b64 s[2:3], s[2:3], exec
	s_bcnt1_i32_b64 s2, s[2:3]
	s_cmp_gt_u32 s2, 15
	s_cselect_b32 s10, s11, s10
	s_or_b32 s11, s10, 0x4000
	v_cmp_le_u32_e32 vcc, s11, v2
	s_and_b64 s[2:3], s[14:15], vcc
	s_and_b64 s[2:3], s[2:3], exec
	s_bcnt1_i32_b64 s2, s[2:3]
	s_cmp_gt_u32 s2, 15
	s_cselect_b32 s10, s11, s10
	s_or_b32 s11, s10, 0x2000
	v_cmp_le_u32_e32 vcc, s11, v2
	s_and_b64 s[2:3], s[14:15], vcc
	s_and_b64 s[2:3], s[2:3], exec
	s_bcnt1_i32_b64 s2, s[2:3]
	s_cmp_gt_u32 s2, 15
	s_cselect_b32 s10, s11, s10
	s_or_b32 s11, s10, 0x1000
	v_cmp_le_u32_e32 vcc, s11, v2
	s_and_b64 s[2:3], s[14:15], vcc
	s_and_b64 s[2:3], s[2:3], exec
	s_bcnt1_i32_b64 s2, s[2:3]
	s_cmp_gt_u32 s2, 15
	s_cselect_b32 s10, s11, s10
	s_or_b32 s11, s10, 0x800
	v_cmp_le_u32_e32 vcc, s11, v2
	s_and_b64 s[2:3], s[14:15], vcc
	s_and_b64 s[2:3], s[2:3], exec
	s_bcnt1_i32_b64 s2, s[2:3]
	s_cmp_gt_u32 s2, 15
	s_cselect_b32 s10, s11, s10
	s_or_b32 s11, s10, 0x400
	v_cmp_le_u32_e32 vcc, s11, v2
	s_and_b64 s[2:3], s[14:15], vcc
	s_and_b64 s[2:3], s[2:3], exec
	s_bcnt1_i32_b64 s2, s[2:3]
	s_cmp_gt_u32 s2, 15
	s_cselect_b32 s10, s11, s10
	s_or_b32 s11, s10, 0x200
	v_cmp_le_u32_e32 vcc, s11, v2
	s_and_b64 s[2:3], s[14:15], vcc
	s_and_b64 s[2:3], s[2:3], exec
	s_bcnt1_i32_b64 s2, s[2:3]
	s_cmp_gt_u32 s2, 15
	s_cselect_b32 s10, s11, s10
	s_or_b32 s11, s10, 0x100
	v_cmp_le_u32_e32 vcc, s11, v2
	s_and_b64 s[2:3], s[14:15], vcc
	s_and_b64 s[2:3], s[2:3], exec
	s_bcnt1_i32_b64 s2, s[2:3]
	s_cmp_gt_u32 s2, 15
	s_cselect_b32 s10, s11, s10
	s_or_b32 s11, s10, 0x80
	v_cmp_le_u32_e32 vcc, s11, v2
	s_and_b64 s[2:3], s[14:15], vcc
	s_and_b64 s[2:3], s[2:3], exec
	s_bcnt1_i32_b64 s2, s[2:3]
	s_cmp_gt_u32 s2, 15
	s_cselect_b32 s10, s11, s10
	s_or_b32 s11, s10, 64
	v_cmp_le_u32_e32 vcc, s11, v2
	s_and_b64 s[2:3], s[14:15], vcc
	s_and_b64 s[2:3], s[2:3], exec
	s_bcnt1_i32_b64 s2, s[2:3]
	s_cmp_gt_u32 s2, 15
	s_cselect_b32 s10, s11, s10
	s_or_b32 s11, s10, 32
	v_cmp_le_u32_e32 vcc, s11, v2
	s_and_b64 s[2:3], s[14:15], vcc
	s_and_b64 s[2:3], s[2:3], exec
	s_bcnt1_i32_b64 s2, s[2:3]
	s_cmp_gt_u32 s2, 15
	s_cselect_b32 s10, s11, s10
	s_or_b32 s11, s10, 16
	v_cmp_le_u32_e32 vcc, s11, v2
	s_and_b64 s[2:3], s[14:15], vcc
	s_and_b64 s[2:3], s[2:3], exec
	s_bcnt1_i32_b64 s2, s[2:3]
	s_cmp_gt_u32 s2, 15
	s_cselect_b32 s10, s11, s10
	s_or_b32 s11, s10, 8
	v_cmp_le_u32_e32 vcc, s11, v2
	s_and_b64 s[2:3], s[14:15], vcc
	s_and_b64 s[2:3], s[2:3], exec
	s_bcnt1_i32_b64 s2, s[2:3]
	s_cmp_gt_u32 s2, 15
	s_cselect_b32 s10, s11, s10
	s_or_b32 s11, s10, 4
	v_cmp_le_u32_e32 vcc, s11, v2
	s_and_b64 s[2:3], s[14:15], vcc
	s_and_b64 s[2:3], s[2:3], exec
	s_bcnt1_i32_b64 s2, s[2:3]
	s_cmp_gt_u32 s2, 15
	s_cselect_b32 s10, s11, s10
	s_or_b32 s11, s10, 2
	v_cmp_le_u32_e32 vcc, s11, v2
	s_and_b64 s[2:3], s[14:15], vcc
	s_and_b64 s[2:3], s[2:3], exec
	s_bcnt1_i32_b64 s2, s[2:3]
	s_cmp_gt_u32 s2, 15
	s_cselect_b32 s10, s11, s10
	s_or_b32 s11, s10, 1
	v_cmp_le_u32_e32 vcc, s11, v2
	s_and_b64 s[2:3], s[14:15], vcc
	s_and_b64 s[2:3], s[2:3], exec
	s_bcnt1_i32_b64 s2, s[2:3]
	s_cmp_gt_u32 s2, 15
	s_cselect_b32 s10, s11, s10
	v_cmp_lt_u32_e32 vcc, s10, v2
	s_and_b64 s[2:3], s[14:15], vcc
	v_cmp_eq_u32_e64 s[22:23], s10, v2
	v_cndmask_b32_e64 v3, 0, 1, s[2:3]
	s_and_b64 s[2:3], s[14:15], s[22:23]
	v_cndmask_b32_e64 v2, 0, 1, s[2:3]
	v_cmp_ne_u32_e64 s[20:21], 0, v3
	v_cmp_ne_u32_e64 s[24:25], 0, v2
	s_bcnt1_i32_b64 s2, s[20:21]
	s_sub_i32 s2, 16, s2
	v_mbcnt_lo_u32_b32 v2, s24, 0
	v_mbcnt_hi_u32_b32 v2, s25, v2
	v_cmp_gt_i32_e64 s[20:21], s2, v2
	s_and_b64 s[2:3], s[22:23], s[20:21]
	v_cndmask_b32_e64 v2, 0, 1, s[2:3]
	s_or_b64 vcc, s[12:13], vcc
	v_cndmask_b32_e32 v2, v2, v8, vcc
	v_and_b32_e32 v2, 1, v2
	v_cmp_ne_u32_e64 s[2:3], 0, v2

; DI void slc_block(const Params& p, int it, int tid, int wid, int lane) {
;     ...
;       const int j = lane;
;       const float4 pq = *reinterpret_cast<const float4*>(psrow + 4 * j);
;       const float sm = (j > 0 ? psrow[4 * j - 1] : 0.f) + pq.x + pq.y + pq.z + pq.w;
;       const bool forced = (j == 0) || (j == blk_t) || (j == blk_t - 1);
;       key = valid ? __float_as_uint(sm + (forced ? 1e4f : 0.f)) : 0u;
;     }
;     unsigned thr = 0u;
;     ...
;       const unsigned cand = thr | (1u << bit);
;       if (__popcll(__ballot(valid && key >= cand)) >= 16) thr = cand;
;     }
;     const unsigned long long gt = __ballot(valid && key > thr), eq = __ballot(valid && key == thr);
;     const int need = 16 - __popcll(gt);
.LBB0_187:
	s_or_b64 exec, exec, s[16:17]
	s_waitcnt vmcnt(0)
	v_add_f32_e32 v2, v2, v9
	v_add_f32_e32 v2, v3, v2
	v_add_f32_e32 v2, v4, v2
	v_add_f32_e32 v2, v5, v2
	v_add_f32_e32 v0, v0, v2
	v_cndmask_b32_e64 v0, 0, v0, s[14:15]
	s_brev_b32 s10, -4
	v_cmp_lt_u32_e32 vcc, s10, v0
	s_and_b64 s[10:11], s[14:15], vcc
	s_and_b64 s[10:11], s[10:11], exec
	s_bcnt1_i32_b64 s10, s[10:11]
	s_cmp_gt_u32 s10, 15
	s_cselect_b32 s16, 2.0, 0
	s_or_b32 s17, s16, 0x20000000
	v_cmp_le_u32_e32 vcc, s17, v0
	s_and_b64 s[10:11], s[14:15], vcc
	s_and_b64 s[10:11], s[10:11], exec
	s_bcnt1_i32_b64 s10, s[10:11]
	s_cmp_gt_u32 s10, 15
	s_cselect_b32 s16, s17, s16
	s_or_b32 s17, s16, 0x10000000
	v_cmp_le_u32_e32 vcc, s17, v0
	s_and_b64 s[10:11], s[14:15], vcc
	s_and_b64 s[10:11], s[10:11], exec
	s_bcnt1_i32_b64 s10, s[10:11]
	s_cmp_gt_u32 s10, 15
	s_cselect_b32 s16, s17, s16
	s_or_b32 s17, s16, 0x8000000
	v_cmp_le_u32_e32 vcc, s17, v0
	s_and_b64 s[10:11], s[14:15], vcc
	s_and_b64 s[10:11], s[10:11], exec
	s_bcnt1_i32_b64 s10, s[10:11]
	s_cmp_gt_u32 s10, 15
	s_cselect_b32 s16, s17, s16
	s_or_b32 s17, s16, 0x4000000
	v_cmp_le_u32_e32 vcc, s17, v0
	s_and_b64 s[10:11], s[14:15], vcc
	s_and_b64 s[10:11], s[10:11], exec
	s_bcnt1_i32_b64 s10, s[10:11]
	s_cmp_gt_u32 s10, 15
	s_cselect_b32 s16, s17, s16
	s_or_b32 s17, s16, 0x2000000
	v_cmp_le_u32_e32 vcc, s17, v0
	s_and_b64 s[10:11], s[14:15], vcc
	s_and_b64 s[10:11], s[10:11], exec
	s_bcnt1_i32_b64 s10, s[10:11]
	s_cmp_gt_u32 s10, 15
	s_cselect_b32 s16, s17, s16
	s_or_b32 s17, s16, 0x1000000
	v_cmp_le_u32_e32 vcc, s17, v0
	s_and_b64 s[10:11], s[14:15], vcc
	s_and_b64 s[10:11], s[10:11], exec
	s_bcnt1_i32_b64 s10, s[10:11]
	s_cmp_gt_u32 s10, 15
	s_cselect_b32 s16, s17, s16
	s_or_b32 s17, s16, 0x800000
	v_cmp_le_u32_e32 vcc, s17, v0
	s_and_b64 s[10:11], s[14:15], vcc
	s_and_b64 s[10:11], s[10:11], exec
	s_bcnt1_i32_b64 s10, s[10:11]
	s_cmp_gt_u32 s10, 15
	s_cselect_b32 s16, s17, s16
	s_or_b32 s17, s16, 0x400000
	v_cmp_le_u32_e32 vcc, s17, v0
	s_and_b64 s[10:11], s[14:15], vcc
	s_and_b64 s[10:11], s[10:11], exec
	s_bcnt1_i32_b64 s10, s[10:11]
	s_cmp_gt_u32 s10, 15
	s_cselect_b32 s16, s17, s16
	s_or_b32 s17, s16, 0x200000
	v_cmp_le_u32_e32 vcc, s17, v0
	s_and_b64 s[10:11], s[14:15], vcc
	s_and_b64 s[10:11], s[10:11], exec
	s_bcnt1_i32_b64 s10, s[10:11]
	s_cmp_gt_u32 s10, 15
	s_cselect_b32 s16, s17, s16
	s_or_b32 s17, s16, 0x100000
	v_cmp_le_u32_e32 vcc, s17, v0
	s_and_b64 s[10:11], s[14:15], vcc
	s_and_b64 s[10:11], s[10:11], exec
	s_bcnt1_i32_b64 s10, s[10:11]
	s_cmp_gt_u32 s10, 15
	s_cselect_b32 s16, s17, s16
	s_or_b32 s17, s16, 0x80000
	v_cmp_le_u32_e32 vcc, s17, v0
	s_and_b64 s[10:11], s[14:15], vcc
	s_and_b64 s[10:11], s[10:11], exec
	s_bcnt1_i32_b64 s10, s[10:11]
	s_cmp_gt_u32 s10, 15
	s_cselect_b32 s16, s17, s16
	s_or_b32 s17, s16, 0x40000
	v_cmp_le_u32_e32 vcc, s17, v0
	s_and_b64 s[10:11], s[14:15], vcc
	s_and_b64 s[10:11], s[10:11], exec
	s_bcnt1_i32_b64 s10, s[10:11]
	s_cmp_gt_u32 s10, 15
	s_cselect_b32 s16, s17, s16
	s_or_b32 s17, s16, 0x20000
	v_cmp_le_u32_e32 vcc, s17, v0
	s_and_b64 s[10:11], s[14:15], vcc
	s_and_b64 s[10:11], s[10:11], exec
	s_bcnt1_i32_b64 s10, s[10:11]
	s_cmp_gt_u32 s10, 15
	s_cselect_b32 s16, s17, s16
	s_or_b32 s17, s16, 0x10000
	v_cmp_le_u32_e32 vcc, s17, v0
	s_and_b64 s[10:11], s[14:15], vcc
	s_and_b64 s[10:11], s[10:11], exec
	s_bcnt1_i32_b64 s10, s[10:11]
	s_cmp_gt_u32 s10, 15
	s_cselect_b32 s16, s17, s16
	s_or_b32 s17, s16, 0x8000
	v_cmp_le_u32_e32 vcc, s17, v0
	s_and_b64 s[10:11], s[14:15], vcc
	s_and_b64 s[10:11], s[10:11], exec
	s_bcnt1_i32_b64 s10, s[10:11]
	s_cmp_gt_u32 s10, 15
	s_cselect_b32 s16, s17, s16
	s_or_b32 s17, s16, 0x4000
	v_cmp_le_u32_e32 vcc, s17, v0
	s_and_b64 s[10:11], s[14:15], vcc
; DI void slc_block(const Params& p, int it, int tid, int wid, int lane) {
;     ...
;     unsigned thr = 0u;
;     ...
;       const unsigned cand = thr | (1u << bit);
;       if (__popcll(__ballot(valid && key >= cand)) >= 16) thr = cand;
;     }
;     const unsigned long long gt = __ballot(valid && key > thr), eq = __ballot(valid && key == thr);
;     const int need = 16 - __popcll(gt);
;     const int idx_eq = (int)__builtin_amdgcn_mbcnt_hi((unsigned)(eq >> 32), __builtin_amdgcn_mbcnt_lo((unsigned)eq, 0u));
;     msel[k] = __ballot(valid && (key > thr || (key == thr && idx_eq < need)));
;   }
	s_and_b64 s[10:11], s[10:11], exec
	s_bcnt1_i32_b64 s10, s[10:11]
	s_cmp_gt_u32 s10, 15
	s_cselect_b32 s16, s17, s16
	s_or_b32 s17, s16, 0x2000
	v_cmp_le_u32_e32 vcc, s17, v0
	s_and_b64 s[10:11], s[14:15], vcc
	s_and_b64 s[10:11], s[10:11], exec
	s_bcnt1_i32_b64 s10, s[10:11]
	s_cmp_gt_u32 s10, 15
	s_cselect_b32 s16, s17, s16
	s_or_b32 s17, s16, 0x1000
	v_cmp_le_u32_e32 vcc, s17, v0
	s_and_b64 s[10:11], s[14:15], vcc
	s_and_b64 s[10:11], s[10:11], exec
	s_bcnt1_i32_b64 s10, s[10:11]
	s_cmp_gt_u32 s10, 15
	s_cselect_b32 s16, s17, s16
	s_or_b32 s17, s16, 0x800
	v_cmp_le_u32_e32 vcc, s17, v0
	s_and_b64 s[10:11], s[14:15], vcc
	s_and_b64 s[10:11], s[10:11], exec
	s_bcnt1_i32_b64 s10, s[10:11]
	s_cmp_gt_u32 s10, 15
	s_cselect_b32 s16, s17, s16
	s_or_b32 s17, s16, 0x400
	v_cmp_le_u32_e32 vcc, s17, v0
	s_and_b64 s[10:11], s[14:15], vcc
	s_and_b64 s[10:11], s[10:11], exec
	s_bcnt1_i32_b64 s10, s[10:11]
	s_cmp_gt_u32 s10, 15
	s_cselect_b32 s16, s17, s16
	s_or_b32 s17, s16, 0x200
	v_cmp_le_u32_e32 vcc, s17, v0
	s_and_b64 s[10:11], s[14:15], vcc
	s_and_b64 s[10:11], s[10:11], exec
	s_bcnt1_i32_b64 s10, s[10:11]
	s_cmp_gt_u32 s10, 15
	s_cselect_b32 s16, s17, s16
	s_or_b32 s17, s16, 0x100
	v_cmp_le_u32_e32 vcc, s17, v0
	s_and_b64 s[10:11], s[14:15], vcc
	s_and_b64 s[10:11], s[10:11], exec
	s_bcnt1_i32_b64 s10, s[10:11]
	s_cmp_gt_u32 s10, 15
	s_cselect_b32 s16, s17, s16
	s_or_b32 s17, s16, 0x80
	v_cmp_le_u32_e32 vcc, s17, v0
	s_and_b64 s[10:11], s[14:15], vcc
	s_and_b64 s[10:11], s[10:11], exec
	s_bcnt1_i32_b64 s10, s[10:11]
	s_cmp_gt_u32 s10, 15
	s_cselect_b32 s16, s17, s16
	s_or_b32 s17, s16, 64
	v_cmp_le_u32_e32 vcc, s17, v0
	s_and_b64 s[10:11], s[14:15], vcc
	s_and_b64 s[10:11], s[10:11], exec
	s_bcnt1_i32_b64 s10, s[10:11]
	s_cmp_gt_u32 s10, 15
	s_cselect_b32 s16, s17, s16
	s_or_b32 s17, s16, 32
	v_cmp_le_u32_e32 vcc, s17, v0
	s_and_b64 s[10:11], s[14:15], vcc
	s_and_b64 s[10:11], s[10:11], exec
	s_bcnt1_i32_b64 s10, s[10:11]
	s_cmp_gt_u32 s10, 15
	s_cselect_b32 s16, s17, s16
	s_or_b32 s17, s16, 16
	v_cmp_le_u32_e32 vcc, s17, v0
	s_and_b64 s[10:11], s[14:15], vcc
	s_and_b64 s[10:11], s[10:11], exec
	s_bcnt1_i32_b64 s10, s[10:11]
	s_cmp_gt_u32 s10, 15
	s_cselect_b32 s16, s17, s16
	s_or_b32 s17, s16, 8
	v_cmp_le_u32_e32 vcc, s17, v0
	s_and_b64 s[10:11], s[14:15], vcc
	s_and_b64 s[10:11], s[10:11], exec
	s_bcnt1_i32_b64 s10, s[10:11]
	s_cmp_gt_u32 s10, 15
	s_cselect_b32 s16, s17, s16
	s_or_b32 s17, s16, 4
	v_cmp_le_u32_e32 vcc, s17, v0
	s_and_b64 s[10:11], s[14:15], vcc
	s_and_b64 s[10:11], s[10:11], exec
	s_bcnt1_i32_b64 s10, s[10:11]
	s_cmp_gt_u32 s10, 15
	s_cselect_b32 s16, s17, s16
	s_or_b32 s17, s16, 2
	v_cmp_le_u32_e32 vcc, s17, v0
	s_and_b64 s[10:11], s[14:15], vcc
	s_and_b64 s[10:11], s[10:11], exec
	s_bcnt1_i32_b64 s10, s[10:11]
	s_cmp_gt_u32 s10, 15
	s_cselect_b32 s16, s17, s16
	s_or_b32 s17, s16, 1
	v_cmp_le_u32_e32 vcc, s17, v0
	s_and_b64 s[10:11], s[14:15], vcc
	s_and_b64 s[10:11], s[10:11], exec
	s_bcnt1_i32_b64 s10, s[10:11]
	s_cmp_gt_u32 s10, 15
	s_cselect_b32 s20, s17, s16
	v_cmp_lt_u32_e32 vcc, s20, v0
	s_and_b64 s[10:11], s[14:15], vcc
	v_cmp_eq_u32_e64 s[20:21], s20, v0
	v_cndmask_b32_e64 v2, 0, 1, s[10:11]
	s_and_b64 s[10:11], s[14:15], s[20:21]
	v_cndmask_b32_e64 v0, 0, 1, s[10:11]
	v_cmp_ne_u32_e64 s[16:17], 0, v2
	v_cmp_ne_u32_e64 s[14:15], 0, v0
	s_bcnt1_i32_b64 s10, s[16:17]
	s_sub_i32 s10, 16, s10
	v_mbcnt_lo_u32_b32 v0, s14, 0
	v_mbcnt_hi_u32_b32 v0, s15, v0
	v_cmp_gt_i32_e64 s[14:15], s10, v0
	s_and_b64 s[10:11], s[20:21], s[14:15]
	v_cndmask_b32_e64 v0, 0, 1, s[10:11]
	s_or_b64 vcc, s[12:13], vcc
	v_cndmask_b32_e32 v0, v0, v8, vcc
	v_and_b32_e32 v0, 1, v0
	v_cmp_ne_u32_e64 s[16:17], 0, v0
	s_branch .LBB0_194

; DI float bflo(unsigned w) { return __uint_as_float(w << 16); }
; DI float bfhi(unsigned w) { return __uint_as_float(w & 0xffff0000u); }
; DI void dil_merge(const Params& p, int gw, int nw, int lane) {
;   const u16* og = (const u16*)(p.ws + OFF_OG);
;   const float* lse = (const float*)(p.ws + OFF_LSE);
;   u16* ya = (u16*)(p.ws + OFF_YA);
;   const int hh = lane >> 4, d0 = (lane & 15) * 8;
;   for (int tok = gw; tok < T_; tok += nw) {
;     const float l0 = lse[((size_t)0 * T_ + tok) * 4 + hh], l1 = lse[((size_t)1 * T_ + tok) * 4 + hh], l2 = lse[((size_t)2 * T_ + tok) * 4 + hh];
;     const float mx = fmaxf(l0, fmaxf(l1, l2));
;     float w0 = __expf(l0 - mx), w1 = __expf(l1 - mx), w2 = __expf(l2 - mx);
;     const float inv = 1.f / (w0 + w1 + w2);
;     w0 *= inv; w1 *= inv; w2 *= inv;
;     const uint4 a0 = *reinterpret_cast<const uint4*>(og + ((size_t)0 * T_ + tok) * 512 + hh * 128 + d0);
;     const uint4 a1 = *reinterpret_cast<const uint4*>(og + ((size_t)1 * T_ + tok) * 512 + hh * 128 + d0);
;     const uint4 a2 = *reinterpret_cast<const uint4*>(og + ((size_t)2 * T_ + tok) * 512 + hh * 128 + d0);
;     uint4 o;
;     o.x = pk2(w0 * bflo(a0.x) + w1 * bflo(a1.x) + w2 * bflo(a2.x), w0 * bfhi(a0.x) + w1 * bfhi(a1.x) + w2 * bfhi(a2.x));
;     o.y = pk2(w0 * bflo(a0.y) + w1 * bflo(a1.y) + w2 * bflo(a2.y), w0 * bfhi(a0.y) + w1 * bfhi(a1.y) + w2 * bfhi(a2.y));
;     o.z = pk2(w0 * bflo(a0.z) + w1 * bflo(a1.z) + w2 * bflo(a2.z), w0 * bfhi(a0.z) + w1 * bfhi(a1.z) + w2 * bfhi(a2.z));
;     o.w = pk2(w0 * bflo(a0.w) + w1 * bflo(a1.w) + w2 * bflo(a2.w), w0 * bfhi(a0.w) + w1 * bfhi(a1.w) + w2 * bfhi(a2.w));
;     *reinterpret_cast<uint4*>(ya + (size_t)tok * 512 + hh * 128 + d0) = o;
;   }
.LBB0_230:
	s_movk_i32 s0, 0x4000
	v_cmp_gt_i32_e32 vcc, s0, v178
	s_and_saveexec_b64 s[0:1], vcc
	s_cbranch_execz .LBB0_233
	v_and_b32_e32 v0, 63, v239
	v_lshrrev_b32_e32 v0, 4, v0
	v_ashrrev_i32_e32 v179, 31, v178
	s_waitcnt vmcnt(0)
	v_and_b32_e32 v5, 15, v239
	v_lshlrev_b64 v[2:3], 10, v[178:179]
	v_lshlrev_b32_e32 v4, 8, v0
	v_lshlrev_b32_e32 v5, 4, v5
	v_or3_b32 v2, v2, v4, v5
	s_ashr_i32 s85, s84, 31
	v_lshlrev_b64 v[4:5], 4, v[178:179]
	s_lshl_b64 s[4:5], s[84:85], 10
	v_lshl_or_b32 v4, v0, 2, v4
	s_lshl_b64 s[6:7], s[84:85], 4
	s_mov_b64 s[8:9], 0
	v_mov_b32_e32 v0, v178
	v_lshl_add_u64 v[6:7], s[74:75], 0, v[4:5]
	v_add_co_u32_e32 v8, vcc, 0x2b920000, v6
	s_nop 1
	v_addc_co_u32_e32 v9, vcc, 0, v7, vcc
	global_load_dword v10, v[8:9], off
	v_add_co_u32_e32 v8, vcc, 0x2b960000, v6
	s_nop 1
	v_addc_co_u32_e32 v9, vcc, 0, v7, vcc
	global_load_dword v11, v[8:9], off
	v_add_co_u32_e32 v8, vcc, 0x2b9a0000, v6
	s_nop 1
	v_addc_co_u32_e32 v9, vcc, 0, v7, vcc
	global_load_dword v12, v[8:9], off
	v_lshl_add_u64 v[24:25], s[74:75], 0, v[2:3]
	v_add_co_u32_e32 v6, vcc, 0x28920000, v24
	s_nop 1
	v_addc_co_u32_e32 v7, vcc, 0, v25, vcc
	global_load_dwordx4 v[32:35], v[6:7], off
	v_add_co_u32_e32 v6, vcc, 0x29920000, v24
	s_nop 1
	v_addc_co_u32_e32 v7, vcc, 0, v25, vcc
	global_load_dwordx4 v[36:39], v[6:7], off
	v_add_co_u32_e32 v6, vcc, 0x2a920000, v24
	s_nop 1
	v_addc_co_u32_e32 v7, vcc, 0, v25, vcc
	global_load_dwordx4 v[40:43], v[6:7], off
.Ldm_loop:
	v_lshl_add_u64 v[26:27], s[74:75], 0, v[2:3]
	v_add_u32_e32 v0, s84, v0
	v_lshl_add_u64 v[2:3], v[2:3], 0, s[4:5]
	v_lshl_add_u64 v[4:5], v[4:5], 0, s[6:7]
	s_waitcnt vmcnt(3)
	v_max3_f32 v13, v10, v11, v12
	v_sub_f32_e32 v14, v10, v13
	v_sub_f32_e32 v15, v11, v13
	v_mul_f32_e32 v14, 0x3fb8aa3b, v14
	v_mul_f32_e32 v15, 0x3fb8aa3b, v15
	v_sub_f32_e32 v16, v12, v13
	v_exp_f32_e32 v19, v14
	v_exp_f32_e32 v18, v15
	v_mul_f32_e32 v16, 0x3fb8aa3b, v16
	v_exp_f32_e32 v16, v16
	v_add_f32_e32 v13, v19, v18
	v_add_f32_e32 v13, v16, v13
	v_div_scale_f32 v14, s[2:3], v13, v13, 1.0
	v_rcp_f32_e32 v15, v14
	s_nop 0
	v_fma_f32 v17, -v14, v15, 1.0
	v_fmac_f32_e32 v15, v17, v15
	v_div_scale_f32 v17, vcc, 1.0, v13, 1.0
	v_mul_f32_e32 v20, v17, v15
	v_fma_f32 v21, -v14, v20, v17
	v_fmac_f32_e32 v20, v21, v15
	v_fma_f32 v14, -v14, v20, v17
	v_div_fmas_f32 v14, v14, v15, v20
	v_div_fixup_f32 v20, v14, v13, 1.0
	v_mul_f32_e32 v22, v16, v20
	v_mul_f32_e32 v19, v19, v20
	v_mul_f32_e32 v18, v18, v20
	v_lshl_add_u64 v[6:7], s[74:75], 0, v[4:5]
	v_add_co_u32_e32 v8, vcc, 0x2b920000, v6
	s_nop 1
	v_addc_co_u32_e32 v9, vcc, 0, v7, vcc
	global_load_dword v10, v[8:9], off
	v_add_co_u32_e32 v8, vcc, 0x2b960000, v6
	s_nop 1
	v_addc_co_u32_e32 v9, vcc, 0, v7, vcc
	global_load_dword v11, v[8:9], off
	v_add_co_u32_e32 v8, vcc, 0x2b9a0000, v6
	s_nop 1
	v_addc_co_u32_e32 v9, vcc, 0, v7, vcc
	global_load_dword v12, v[8:9], off
	s_waitcnt vmcnt(3)
	v_lshlrev_b32_e32 v13, 16, v32
	v_and_b32_e32 v14, 0xffff0000, v36
	v_lshlrev_b32_e32 v15, 16, v36
	v_and_b32_e32 v16, 0xffff0000, v32
	v_lshlrev_b32_e32 v17, 16, v40
	v_and_b32_e32 v20, 0xffff0000, v40
	v_mul_f32_e32 v13, v19, v13
	v_mul_f32_e32 v14, v18, v14
	v_fmac_f32_e32 v13, v18, v15
	v_fmac_f32_e32 v14, v19, v16
	v_fmac_f32_e32 v13, v22, v17
	v_fmac_f32_e32 v14, v22, v20
	v_cvt_pk_bf16_f32 v44, v13, v14
	v_lshlrev_b32_e32 v13, 16, v33
	v_and_b32_e32 v14, 0xffff0000, v37
	v_lshlrev_b32_e32 v15, 16, v37
	v_and_b32_e32 v16, 0xffff0000, v33
	v_lshlrev_b32_e32 v17, 16, v41
	v_and_b32_e32 v20, 0xffff0000, v41
	v_mul_f32_e32 v13, v19, v13
	v_mul_f32_e32 v14, v18, v14
	v_fmac_f32_e32 v13, v18, v15
	v_fmac_f32_e32 v14, v19, v16
	v_fmac_f32_e32 v13, v22, v17
	v_fmac_f32_e32 v14, v22, v20
	v_cvt_pk_bf16_f32 v45, v13, v14
	v_lshlrev_b32_e32 v13, 16, v34
	v_and_b32_e32 v14, 0xffff0000, v38
	v_lshlrev_b32_e32 v15, 16, v38
	v_and_b32_e32 v16, 0xffff0000, v34
	v_lshlrev_b32_e32 v17, 16, v42
	v_and_b32_e32 v20, 0xffff0000, v42
	v_mul_f32_e32 v13, v19, v13
	v_mul_f32_e32 v14, v18, v14
	v_fmac_f32_e32 v13, v18, v15
	v_fmac_f32_e32 v14, v19, v16
	v_fmac_f32_e32 v13, v22, v17
	v_fmac_f32_e32 v14, v22, v20
	v_cvt_pk_bf16_f32 v46, v13, v14
	v_lshlrev_b32_e32 v13, 16, v35
	v_and_b32_e32 v14, 0xffff0000, v39
	v_lshlrev_b32_e32 v15, 16, v39
	v_and_b32_e32 v16, 0xffff0000, v35
	v_lshlrev_b32_e32 v17, 16, v43
	v_and_b32_e32 v20, 0xffff0000, v43
	v_mul_f32_e32 v13, v19, v13
	v_mul_f32_e32 v14, v18, v14
	v_fmac_f32_e32 v13, v18, v15
	v_fmac_f32_e32 v14, v19, v16
	v_fmac_f32_e32 v13, v22, v17
	v_fmac_f32_e32 v14, v22, v20
	v_cvt_pk_bf16_f32 v47, v13, v14
	v_lshl_add_u64 v[24:25], s[74:75], 0, v[2:3]
	v_add_co_u32_e32 v6, vcc, 0x28920000, v24
	s_nop 1
	v_addc_co_u32_e32 v7, vcc, 0, v25, vcc
	global_load_dwordx4 v[32:35], v[6:7], off
	v_add_co_u32_e32 v6, vcc, 0x29920000, v24
	s_nop 1
	v_addc_co_u32_e32 v7, vcc, 0, v25, vcc
	global_load_dwordx4 v[36:39], v[6:7], off
	v_add_co_u32_e32 v6, vcc, 0x2a920000, v24
	s_nop 1
	v_addc_co_u32_e32 v7, vcc, 0, v25, vcc
	global_load_dwordx4 v[40:43], v[6:7], off
	v_add_co_u32_e32 v6, vcc, 0x2000000, v26
	s_nop 1
	v_addc_co_u32_e32 v7, vcc, 0, v27, vcc
	v_cmp_lt_i32_e32 vcc, s36, v0
	s_or_b64 s[8:9], vcc, s[8:9]
	global_store_dwordx4 v[6:7], v[44:47], off
	s_andn2_b64 exec, exec, s[8:9]
	s_cbranch_execnz .Ldm_loop
	s_waitcnt vmcnt(0)
